# E4 + PV: batch-2 V-fragment ds_reads issued behind the batch-1 MFMAs (counted lgkmcnt(7))
# baseline (speedup 1.0000x reference)
.LBB0_902:
	s_add_i32 s29, s29, 0x10000
	v_add_u32_e32 v179, s29, v189
	v_add_u32_e32 v203, s29, v190
	v_add_u32_e32 v204, s29, v191
	v_add_u32_e32 v205, s29, v192
	ds_read_b128 v[96:99], v179
	ds_read_b128 v[100:103], v179 offset:4096
	ds_read_b128 v[104:107], v203
	ds_read_b128 v[108:111], v203 offset:4096
	ds_read_b128 v[112:115], v204
	ds_read_b128 v[116:119], v204 offset:4096
	ds_read_b128 v[120:123], v205
	ds_read_b128 v[124:127], v205 offset:4096
	s_setprio 1
	s_waitcnt lgkmcnt(7)
	v_mfma_f32_32x32x16_bf16 v[16:31], v[96:99], v[144:147], v[16:31]
	ds_read_b128 v[96:99], v179 offset:8192
	s_waitcnt lgkmcnt(7)
	v_mfma_f32_32x32x16_bf16 v[48:63], v[100:103], v[144:147], v[48:63]
	ds_read_b128 v[100:103], v179 offset:12288
	s_waitcnt lgkmcnt(7)
	v_mfma_f32_32x32x16_bf16 v[16:31], v[104:107], v[148:151], v[16:31]
	ds_read_b128 v[104:107], v203 offset:8192
	s_waitcnt lgkmcnt(7)
	v_mfma_f32_32x32x16_bf16 v[48:63], v[108:111], v[148:151], v[48:63]
	ds_read_b128 v[108:111], v203 offset:12288
	s_waitcnt lgkmcnt(7)
	v_mfma_f32_32x32x16_bf16 v[16:31], v[112:115], v[152:155], v[16:31]
	ds_read_b128 v[112:115], v204 offset:8192
	s_waitcnt lgkmcnt(7)
	v_mfma_f32_32x32x16_bf16 v[48:63], v[116:119], v[152:155], v[48:63]
	ds_read_b128 v[116:119], v204 offset:12288
	s_waitcnt lgkmcnt(7)
	v_mfma_f32_32x32x16_bf16 v[16:31], v[120:123], v[156:159], v[16:31]
	ds_read_b128 v[120:123], v205 offset:8192
	s_waitcnt lgkmcnt(7)
	v_mfma_f32_32x32x16_bf16 v[48:63], v[124:127], v[156:159], v[48:63]
	ds_read_b128 v[124:127], v205 offset:12288
	s_waitcnt lgkmcnt(7)
	v_mfma_f32_32x32x16_bf16 v[32:47], v[96:99], v[144:147], v[32:47]
	s_waitcnt lgkmcnt(6)
	v_mfma_f32_32x32x16_bf16 v[0:15], v[100:103], v[144:147], v[0:15]
	s_waitcnt lgkmcnt(5)
	v_mfma_f32_32x32x16_bf16 v[32:47], v[104:107], v[148:151], v[32:47]
	s_waitcnt lgkmcnt(4)
	v_mfma_f32_32x32x16_bf16 v[0:15], v[108:111], v[148:151], v[0:15]
	s_waitcnt lgkmcnt(3)
	v_mfma_f32_32x32x16_bf16 v[32:47], v[112:115], v[152:155], v[32:47]
	s_waitcnt lgkmcnt(2)
	v_mfma_f32_32x32x16_bf16 v[0:15], v[116:119], v[152:155], v[0:15]
	s_waitcnt lgkmcnt(1)
	v_mfma_f32_32x32x16_bf16 v[32:47], v[120:123], v[156:159], v[32:47]
	s_waitcnt lgkmcnt(0)
	v_mfma_f32_32x32x16_bf16 v[0:15], v[124:127], v[156:159], v[0:15]
	s_setprio 0

.LBB0_916:
	s_add_i32 s27, s27, 0x10000
	v_add_u32_e32 v96, s27, v189
	v_add_u32_e32 v97, s27, v190
	v_add_u32_e32 v98, s27, v191
	v_add_u32_e32 v99, s27, v192
	ds_read_b128 v[64:67], v96
	ds_read_b128 v[68:71], v96 offset:4096
	ds_read_b128 v[72:75], v97
	ds_read_b128 v[76:79], v97 offset:4096
	ds_read_b128 v[80:83], v98
	ds_read_b128 v[84:87], v98 offset:4096
	ds_read_b128 v[88:91], v99
	ds_read_b128 v[92:95], v99 offset:4096
	s_setprio 1
	s_waitcnt lgkmcnt(7)
	v_mfma_f32_32x32x16_bf16 v[16:31], v[64:67], v[144:147], v[16:31]
	ds_read_b128 v[64:67], v96 offset:8192
	s_waitcnt lgkmcnt(7)
	v_mfma_f32_32x32x16_bf16 v[48:63], v[68:71], v[144:147], v[48:63]
	ds_read_b128 v[68:71], v96 offset:12288
	s_waitcnt lgkmcnt(7)
	v_mfma_f32_32x32x16_bf16 v[16:31], v[72:75], v[148:151], v[16:31]
	ds_read_b128 v[72:75], v97 offset:8192
	s_waitcnt lgkmcnt(7)
	v_mfma_f32_32x32x16_bf16 v[48:63], v[76:79], v[148:151], v[48:63]
	ds_read_b128 v[76:79], v97 offset:12288
	s_waitcnt lgkmcnt(7)
	v_mfma_f32_32x32x16_bf16 v[16:31], v[80:83], v[152:155], v[16:31]
	ds_read_b128 v[80:83], v98 offset:8192
	s_waitcnt lgkmcnt(7)
	v_mfma_f32_32x32x16_bf16 v[48:63], v[84:87], v[152:155], v[48:63]
	ds_read_b128 v[84:87], v98 offset:12288
	s_waitcnt lgkmcnt(7)
	v_mfma_f32_32x32x16_bf16 v[16:31], v[88:91], v[156:159], v[16:31]
	ds_read_b128 v[88:91], v99 offset:8192
	s_waitcnt lgkmcnt(7)
	v_mfma_f32_32x32x16_bf16 v[48:63], v[92:95], v[156:159], v[48:63]
	ds_read_b128 v[92:95], v99 offset:12288
	s_waitcnt lgkmcnt(7)
	v_mfma_f32_32x32x16_bf16 v[32:47], v[64:67], v[144:147], v[32:47]
	s_waitcnt lgkmcnt(6)
	v_mfma_f32_32x32x16_bf16 v[0:15], v[68:71], v[144:147], v[0:15]
	s_waitcnt lgkmcnt(5)
	v_mfma_f32_32x32x16_bf16 v[32:47], v[72:75], v[148:151], v[32:47]
	s_waitcnt lgkmcnt(4)
	v_mfma_f32_32x32x16_bf16 v[0:15], v[76:79], v[148:151], v[0:15]
	s_waitcnt lgkmcnt(3)
	v_mfma_f32_32x32x16_bf16 v[32:47], v[80:83], v[152:155], v[32:47]
	s_waitcnt lgkmcnt(2)
	v_mfma_f32_32x32x16_bf16 v[0:15], v[84:87], v[152:155], v[0:15]
	s_waitcnt lgkmcnt(1)
	v_mfma_f32_32x32x16_bf16 v[32:47], v[88:91], v[156:159], v[32:47]
	s_waitcnt lgkmcnt(0)
	v_mfma_f32_32x32x16_bf16 v[0:15], v[92:95], v[156:159], v[0:15]
	s_setprio 0
	s_branch .LBB0_883
